# baseline (speedup 1.0000x reference)
; DEV void finishSM(f32x16& p0, f32x16& p1, float alpha, float& l_reg, bf16x8& pa0, bf16x8& pa1, bf16x8& pa2, bf16x8& pa3) {
; #pragma unroll
;   for (int r = 0; r < 16; ++r) p1[r] = __builtin_amdgcn_exp2f(p1[r]);
;   float ps = 0;
; #pragma unroll
;   for (int r = 0; r < 16; ++r) ps += p0[r];
; #pragma unroll
;   for (int r = 0; r < 16; ++r) ps += p1[r];
;   { auto rr = __builtin_amdgcn_permlane32_swap(__float_as_uint(ps), __float_as_uint(ps), false, false);
;     ps = __uint_as_float(rr[0]) + __uint_as_float(rr[1]); }
;   l_reg = l_reg * alpha + ps;
;     ...
;   PK4(p0, 0, pa0); PK4(p0, 8, pa1); PK4(p1, 0, pa2); PK4(p1, 8, pa3);
; DEV void qkt(f32x16& p0, f32x16& p1, const char* Ks, const char* KPs, const bf16x8* qr, const char* qpl, int r32, int hi) {
;   p0 = f32x16{}; p1 = f32x16{};
; #pragma unroll
;   for (int d0 = 0; d0 < 8; ++d0) { int cb = (d0 * 16 + hi * 8) * 2;
;     bf16x8 b0 = *reinterpret_cast<const bf16x8*>(Ks + KSWZ(r32, cb));
;     bf16x8 b1 = *reinterpret_cast<const bf16x8*>(Ks + KSWZ(32 + r32, cb));
;     bf16x8 qq = d0 < NQR ? qr[d0 < NQR ? d0 : 0] : *reinterpret_cast<const bf16x8*>(qpl + (d0 - NQR) * 1024);
;     p0 = __builtin_amdgcn_mfma_f32_32x32x16_bf16(b0, qq, p0, 0, 0, 0);
;     p1 = __builtin_amdgcn_mfma_f32_32x32x16_bf16(b1, qq, p1, 0, 0, 0); }
; #pragma unroll
;   for (int d1 = 0; d1 < 4; ++d1) { int cb = (d1 * 16 + hi * 8) * 2;
;     bf16x8 b0 = *reinterpret_cast<const bf16x8*>(KPs + KPSWZ(r32, cb));
;     bf16x8 b1 = *reinterpret_cast<const bf16x8*>(KPs + KPSWZ(32 + r32, cb));
;     bf16x8 qp = *reinterpret_cast<const bf16x8*>(qpl + (8 - NQR + d1) * 1024);
;     p0 = __builtin_amdgcn_mfma_f32_32x32x16_bf16(b0, qp, p0, 0, 0, 0);
;     p1 = __builtin_amdgcn_mfma_f32_32x32x16_bf16(b1, qp, p1, 0, 0, 0); }
; }
.LBB0_304:
	ds_read_b128 v[64:67], v159 offset:49152
	ds_read_b128 v[68:71], v159 offset:57344
	ds_read_b128 v[188:191], v162 offset:49152
	ds_read_b128 v[202:205], v162 offset:57344
	s_waitcnt vmcnt(0)
	ds_write_b128 v154, v[238:241] offset:16384
	ds_write_b128 v155, v[242:245] offset:16384
	s_mov_b32 s0, 0x40000
	v_add_co_u32_e32 v224, vcc, s0, v142
	s_nop 1
	v_addc_co_u32_e32 v225, vcc, 0, v143, vcc
	global_load_dwordx4 v[226:229], v[142:143], off
	global_load_dwordx4 v[230:233], v[224:225], off
	global_load_dwordx4 v[234:237], v[140:141], off
	global_load_dwordx4 v[238:241], v[142:143], off offset:256
	global_load_dwordx4 v[242:245], v[224:225], off offset:256
	v_add_f32_e32 v133, 0, v196
	v_add_f32_e32 v133, v199, v133
	s_waitcnt lgkmcnt(5)
	v_mfma_f32_32x32x16_bf16 v[80:95], v[64:67], v[108:111], 0
	v_add_f32_e32 v133, v197, v133
	v_add_f32_e32 v133, v200, v133
	v_add_f32_e32 v133, v198, v133
	v_add_f32_e32 v133, v201, v133
	v_add_f32_e32 v133, v194, v133
	v_add_f32_e32 v133, v195, v133
	v_add_f32_e32 v133, v134, v133
	s_waitcnt lgkmcnt(4)
	v_mfma_f32_32x32x16_bf16 v[64:79], v[68:71], v[108:111], 0
	v_add_f32_e32 v133, v192, v133
	v_add_f32_e32 v133, v135, v133
	v_add_f32_e32 v133, v193, v133
	v_exp_f32_e32 v126, v126
	v_add_f32_e32 v133, v128, v133
	v_exp_f32_e32 v127, v127
	v_add_f32_e32 v133, v130, v133
	s_waitcnt lgkmcnt(0)
	v_mfma_f32_32x32x16_bf16 v[64:79], v[202:205], v[104:107], v[64:79]
	v_exp_f32_e32 v124, v124
	v_add_f32_e32 v133, v129, v133
	v_exp_f32_e32 v125, v125
	v_add_f32_e32 v133, v131, v133
	v_or_b32_e32 v187, 0x12000, v175
	v_exp_f32_e32 v120, v120
	v_add_f32_e32 v133, v126, v133
	v_mfma_f32_32x32x16_bf16 v[80:95], v[188:191], v[104:107], v[80:95]
	ds_read_b128 v[188:191], v163 offset:49152
	ds_read_b128 v[202:205], v163 offset:57344
	v_exp_f32_e32 v121, v121
	v_add_f32_e32 v133, v127, v133
	v_exp_f32_e32 v116, v116
	v_add_f32_e32 v133, v124, v133
	v_exp_f32_e32 v117, v117
	v_add_f32_e32 v133, v125, v133
	s_waitcnt lgkmcnt(0)
	v_mfma_f32_32x32x16_bf16 v[64:79], v[202:205], v[100:103], v[64:79]
	v_exp_f32_e32 v112, v112
	v_add_f32_e32 v133, v120, v133
	v_exp_f32_e32 v113, v113
	v_add_f32_e32 v133, v121, v133
	v_exp_f32_e32 v122, v122
	v_add_f32_e32 v133, v116, v133
	v_exp_f32_e32 v123, v123
	v_mfma_f32_32x32x16_bf16 v[80:95], v[188:191], v[100:103], v[80:95]
	ds_read_b128 v[188:191], v166 offset:49152
	ds_read_b128 v[202:205], v166 offset:57344
	v_add_f32_e32 v133, v117, v133
	v_exp_f32_e32 v118, v118
	v_add_f32_e32 v133, v112, v133
	v_exp_f32_e32 v119, v119
	v_add_f32_e32 v133, v113, v133
	v_exp_f32_e32 v114, v114
	s_waitcnt lgkmcnt(0)
	v_mfma_f32_32x32x16_bf16 v[64:79], v[202:205], v[96:99], v[64:79]
	v_add_f32_e32 v133, v122, v133
	v_exp_f32_e32 v115, v115
	v_add_f32_e32 v133, v123, v133
	v_add_f32_e32 v133, v118, v133
	v_add_f32_e32 v133, v119, v133
	v_add_f32_e32 v133, v114, v133
	v_mfma_f32_32x32x16_bf16 v[80:95], v[188:191], v[96:99], v[80:95]
	ds_read_b128 v[188:191], v167 offset:49152
	ds_read_b128 v[202:205], v167 offset:57344
	ds_read_b128 v[206:209], v177
	s_waitcnt lgkmcnt(0)
	v_mfma_f32_32x32x16_bf16 v[64:79], v[202:205], v[206:209], v[64:79]
	v_mfma_f32_32x32x16_bf16 v[80:95], v[188:191], v[206:209], v[80:95]
	ds_read_b128 v[188:191], v168 offset:49152
	ds_read_b128 v[202:205], v168 offset:57344
	ds_read_b128 v[206:209], v177 offset:1024
	s_waitcnt lgkmcnt(0)
	v_mfma_f32_32x32x16_bf16 v[64:79], v[202:205], v[206:209], v[64:79]
	v_mfma_f32_32x32x16_bf16 v[80:95], v[188:191], v[206:209], v[80:95]
	ds_read_b128 v[188:191], v160 offset:49152
	ds_read_b128 v[202:205], v160 offset:57344
	ds_read_b128 v[206:209], v177 offset:2048
	s_waitcnt lgkmcnt(0)
	v_mfma_f32_32x32x16_bf16 v[64:79], v[202:205], v[206:209], v[64:79]
	v_mfma_f32_32x32x16_bf16 v[80:95], v[188:191], v[206:209], v[80:95]
	ds_read_b128 v[188:191], v161 offset:49152
	ds_read_b128 v[202:205], v161 offset:57344
	ds_read_b128 v[206:209], v177 offset:3072
	s_waitcnt lgkmcnt(0)
	v_mfma_f32_32x32x16_bf16 v[64:79], v[202:205], v[206:209], v[64:79]
	v_mfma_f32_32x32x16_bf16 v[80:95], v[188:191], v[206:209], v[80:95]
	ds_read_b128 v[188:191], v184
	ds_read_b128 v[202:205], v185
	ds_read_b128 v[206:209], v177 offset:4096
	s_waitcnt lgkmcnt(0)
	v_mfma_f32_32x32x16_bf16 v[64:79], v[202:205], v[206:209], v[64:79]
	v_mfma_f32_32x32x16_bf16 v[80:95], v[188:191], v[206:209], v[80:95]
	ds_read_b128 v[188:191], v181
	ds_read_b128 v[202:205], v182
	ds_read_b128 v[206:209], v177 offset:5120
	s_waitcnt lgkmcnt(0)
	v_mfma_f32_32x32x16_bf16 v[64:79], v[202:205], v[206:209], v[64:79]
	v_mfma_f32_32x32x16_bf16 v[80:95], v[188:191], v[206:209], v[80:95]
	ds_read_b128 v[188:191], v179
	ds_read_b128 v[202:205], v180
	ds_read_b128 v[206:209], v177 offset:6144
	s_waitcnt lgkmcnt(0)
	v_mfma_f32_32x32x16_bf16 v[64:79], v[202:205], v[206:209], v[64:79]
	ds_read_b128 v[202:205], v187
	v_mfma_f32_32x32x16_bf16 v[80:95], v[188:191], v[206:209], v[80:95]
	v_or_b32_e32 v188, 0x13000, v175
	ds_read_b128 v[206:209], v188
	ds_read_b128 v[210:213], v177 offset:7168
	v_add_f32_e32 v189, v115, v133
	v_mov_b32_e32 v190, v189
	s_nop 1
	v_permlane32_swap_b32_e32 v189, v190
	v_cvt_pk_bf16_f32 v196, v196, v199
	s_waitcnt lgkmcnt(0)
; #define SBAR() __builtin_amdgcn_sched_barrier(0)
; DEV void partialSM(f32x16& p0, f32x16& p1, float& m_reg, float& mn, float& alpha) {
;   constexpr float C = SCALE * 1.4426950408889634f;
;   float pmax = p0[0];
; #pragma unroll
;   for (int r = 1; r < 16; ++r) pmax = fmaxf(pmax, p0[r]);
; #pragma unroll
;   for (int r = 0; r < 16; ++r) pmax = fmaxf(pmax, p1[r]);
;   { auto rr = __builtin_amdgcn_permlane32_swap(__float_as_uint(pmax), __float_as_uint(pmax), false, false);
;     pmax = fmaxf(__uint_as_float(rr[0]), __uint_as_float(rr[1])); }
;   if (__builtin_expect(__all(pmax - m_reg <= THR / SCALE), 1)) { mn = m_reg; alpha = 1.f; }
;   else { mn = fmaxf(m_reg, pmax); alpha = __builtin_amdgcn_exp2f((m_reg - mn) * C); m_reg = mn; }
;   float mnC = -mn * C;
; #pragma unroll
;   for (int r = 0; r < 16; ++r) p0[r] = fmaf(p0[r], C, mnC);
; #pragma unroll
;   for (int r = 0; r < 16; ++r) p1[r] = fmaf(p1[r], C, mnC);
; #pragma unroll
;   for (int r = 0; r < 16; ++r) p0[r] = __builtin_amdgcn_exp2f(p0[r]);
; }
; template <int OFF> DEV s16x4 tr_read(int vb) {
;   s16x4 r; asm volatile("ds_read_b64_tr_b16 %0, %1 offset:%2" : "=&v"(r) : "v"(vb), "i"(OFF) : "memory"); return r;
; }
; template <int D0> DEV void pv_one(f32x16& od, int vb, bf16x8 pa0, bf16x8 pa1, bf16x8 pa2, bf16x8 pa3) {
;   const s16x4 l0 = tr_read<v_rd_off(D0, 0, 0)>(vb), h0 = tr_read<v_rd_off(D0, 0, 1)>(vb), l1 = tr_read<v_rd_off(D0, 1, 0)>(vb), h1 = tr_read<v_rd_off(D0, 1, 1)>(vb);
;   const s16x4 l2 = tr_read<v_rd_off(D0, 2, 0)>(vb), h2 = tr_read<v_rd_off(D0, 2, 1)>(vb), l3 = tr_read<v_rd_off(D0, 3, 0)>(vb), h3 = tr_read<v_rd_off(D0, 3, 1)>(vb);
;   asm volatile("s_waitcnt lgkmcnt(0)" ::: "memory"); SBAR();
;     ...
;   od = __builtin_amdgcn_mfma_f32_32x32x16_bf16(pa0, PK(l0, h0), od, 0, 0, 0);
;   od = __builtin_amdgcn_mfma_f32_32x32x16_bf16(pa1, PK(l1, h1), od, 0, 0, 0);
;   od = __builtin_amdgcn_mfma_f32_32x32x16_bf16(pa2, PK(l2, h2), od, 0, 0, 0);
;   od = __builtin_amdgcn_mfma_f32_32x32x16_bf16(pa3, PK(l3, h3), od, 0, 0, 0);
;     ...
; }
; DEV void pv_d0(f32x16* o, int vb, bf16x8 pa0, bf16x8 pa1, bf16x8 pa2, bf16x8 pa3) {
;   pv_one<0>(o[0], vb, pa0, pa1, pa2, pa3); pv_one<1>(o[1], vb, pa0, pa1, pa2, pa3); pv_one<2>(o[2], vb, pa0, pa1, pa2, pa3); pv_one<3>(o[3], vb, pa0, pa1, pa2, pa3);
	v_mfma_f32_32x32x16_bf16 v[80:95], v[202:205], v[210:213], v[80:95]
	v_cvt_pk_bf16_f32 v197, v197, v200
	v_cvt_pk_bf16_f32 v198, v198, v201
	v_cvt_pk_bf16_f32 v199, v194, v195
	v_cvt_pk_bf16_f32 v192, v134, v192
	v_cvt_pk_bf16_f32 v193, v135, v193
	v_cvt_pk_bf16_f32 v194, v128, v130
	v_cvt_pk_bf16_f32 v195, v129, v131
	v_mfma_f32_32x32x16_bf16 v[64:79], v[206:209], v[210:213], v[64:79]
	v_cvt_pk_bf16_f32 v200, v126, v127
	v_cvt_pk_bf16_f32 v201, v124, v125
	v_cvt_pk_bf16_f32 v202, v120, v121
	v_cvt_pk_bf16_f32 v203, v116, v117
	v_cvt_pk_bf16_f32 v204, v112, v113
	v_cvt_pk_bf16_f32 v205, v122, v123
	v_cvt_pk_bf16_f32 v206, v118, v119
	v_cvt_pk_bf16_f32 v207, v114, v115
	v_permlane32_swap_b32_e32 v196, v198
	v_permlane32_swap_b32_e32 v197, v199
	v_permlane32_swap_b32_e32 v192, v194
	v_permlane32_swap_b32_e32 v193, v195
	v_permlane32_swap_b32_e32 v200, v202
	v_permlane32_swap_b32_e32 v201, v203
	v_permlane32_swap_b32_e32 v204, v206
	v_permlane32_swap_b32_e32 v205, v207
	s_waitcnt vmcnt(2)
	ds_write_b128 v156, v[226:229] offset:32768
	ds_write_b128 v157, v[230:233] offset:32768
	ds_write_b128 v158, v[234:237]
	ds_read_b64_tr_b16 v[208:209], v153 offset:0
	ds_read_b64_tr_b16 v[210:211], v153 offset:0x800
	ds_read_b64_tr_b16 v[212:213], v153 offset:0x1000
	ds_read_b64_tr_b16 v[214:215], v153 offset:0x1800
	ds_read_b64_tr_b16 v[216:217], v153 offset:0x2000
	ds_read_b64_tr_b16 v[218:219], v153 offset:0x2800
	ds_read_b64_tr_b16 v[220:221], v153 offset:0x3000
	ds_read_b64_tr_b16 v[222:223], v153 offset:0x3800
	s_waitcnt lgkmcnt(6)
	s_nop 0
	v_mfma_f32_32x32x16_bf16 v[0:15], v[196:199], v[208:211], v[0:15]
	ds_read_b64_tr_b16 v[208:209], v153 offset:0x200
	ds_read_b64_tr_b16 v[210:211], v153 offset:0xa00
	v_max_f32_e32 v133, v81, v81
	v_max_f32_e32 v134, v80, v80
	v_max_f32_e32 v133, v134, v133
	v_max3_f32 v133, v133, v82, v83
	v_max3_f32 v133, v133, v84, v85
	s_waitcnt lgkmcnt(6)
	v_mfma_f32_32x32x16_bf16 v[0:15], v[192:195], v[212:215], v[0:15]
	ds_read_b64_tr_b16 v[212:213], v153 offset:0x1200
	ds_read_b64_tr_b16 v[214:215], v153 offset:0x1a00
	v_max3_f32 v133, v133, v86, v87
	v_max3_f32 v133, v133, v88, v89
	v_max3_f32 v133, v133, v90, v91
	v_max3_f32 v133, v133, v92, v93
	v_max3_f32 v133, v133, v94, v95
	v_max3_f32 v133, v133, v64, v65
	s_waitcnt lgkmcnt(6)
	v_mfma_f32_32x32x16_bf16 v[0:15], v[200:203], v[216:219], v[0:15]
	ds_read_b64_tr_b16 v[216:217], v153 offset:0x2200
	ds_read_b64_tr_b16 v[218:219], v153 offset:0x2a00
	v_max3_f32 v133, v133, v66, v67
	v_max3_f32 v133, v133, v68, v69
	v_max3_f32 v133, v133, v70, v71
	v_max3_f32 v133, v133, v72, v73
	v_max3_f32 v133, v133, v74, v75
	s_waitcnt lgkmcnt(6)
	v_mfma_f32_32x32x16_bf16 v[0:15], v[204:207], v[220:223], v[0:15]
	ds_read_b64_tr_b16 v[220:221], v153 offset:0x3200
	ds_read_b64_tr_b16 v[222:223], v153 offset:0x3a00
	v_max3_f32 v133, v133, v76, v77
	v_max3_f32 v133, v133, v78, v79
	v_mov_b32_e32 v134, v133
	s_nop 1
	s_waitcnt lgkmcnt(6)
	v_mfma_f32_32x32x16_bf16 v[48:63], v[196:199], v[208:211], v[48:63]
	ds_read_b64_tr_b16 v[208:209], v153 offset:0x400
	ds_read_b64_tr_b16 v[210:211], v153 offset:0xc00
	v_permlane32_swap_b32_e32 v133, v134
	v_max_f32_e32 v134, v134, v134
	v_max_f32_e32 v133, v133, v133
	v_max_f32_e32 v133, v133, v134
	v_sub_f32_e32 v134, v133, v132
	v_cmp_ge_f32_e32 vcc, s72, v134
	s_waitcnt lgkmcnt(6)
	v_mfma_f32_32x32x16_bf16 v[48:63], v[192:195], v[212:215], v[48:63]
	ds_read_b64_tr_b16 v[212:213], v153 offset:0x1400
	ds_read_b64_tr_b16 v[214:215], v153 offset:0x1c00
	v_max_f32_e32 v134, v132, v132
	v_max_f32_e32 v133, v134, v133
	v_sub_f32_e32 v134, v132, v133
	v_mul_f32_e32 v134, 0x3dd53b94, v134
	s_waitcnt lgkmcnt(6)
	v_mfma_f32_32x32x16_bf16 v[48:63], v[200:203], v[216:219], v[48:63]
	ds_read_b64_tr_b16 v[216:217], v153 offset:0x2400
	ds_read_b64_tr_b16 v[218:219], v153 offset:0x2c00
	v_exp_f32_e32 v134, v134
	s_cmp_eq_u64 vcc, exec
	s_cselect_b64 s[4:5], -1, 0
	v_cndmask_b32_e64 v226, v133, v132, s[4:5]
	v_mul_f32_e32 v227, 0xbdd53b94, v226
	s_waitcnt lgkmcnt(6)
	v_mfma_f32_32x32x16_bf16 v[48:63], v[204:207], v[220:223], v[48:63]
	ds_read_b64_tr_b16 v[220:221], v153 offset:0x3400
	ds_read_b64_tr_b16 v[222:223], v153 offset:0x3c00
	v_fmamk_f32 v80, v80, 0x3dd53b94, v227
	v_fmamk_f32 v81, v81, 0x3dd53b94, v227
	v_fmamk_f32 v82, v82, 0x3dd53b94, v227
	v_fmamk_f32 v83, v83, 0x3dd53b94, v227
	v_fmamk_f32 v84, v84, 0x3dd53b94, v227
	v_fmamk_f32 v85, v85, 0x3dd53b94, v227
	s_waitcnt lgkmcnt(6)
	v_mfma_f32_32x32x16_bf16 v[32:47], v[196:199], v[208:211], v[32:47]
	ds_read_b64_tr_b16 v[208:209], v153 offset:0x600
	ds_read_b64_tr_b16 v[210:211], v153 offset:0xe00
	v_fmamk_f32 v86, v86, 0x3dd53b94, v227
	v_fmamk_f32 v87, v87, 0x3dd53b94, v227
	v_fmamk_f32 v88, v88, 0x3dd53b94, v227
	v_fmamk_f32 v89, v89, 0x3dd53b94, v227
	v_fmamk_f32 v90, v90, 0x3dd53b94, v227
	s_waitcnt lgkmcnt(6)
	v_mfma_f32_32x32x16_bf16 v[32:47], v[192:195], v[212:215], v[32:47]
	ds_read_b64_tr_b16 v[212:213], v153 offset:0x1600
	ds_read_b64_tr_b16 v[214:215], v153 offset:0x1e00
	v_fmamk_f32 v91, v91, 0x3dd53b94, v227
	v_fmamk_f32 v92, v92, 0x3dd53b94, v227
	v_fmamk_f32 v93, v93, 0x3dd53b94, v227
	v_fmamk_f32 v94, v94, 0x3dd53b94, v227
	v_fmamk_f32 v95, v95, 0x3dd53b94, v227
	s_waitcnt lgkmcnt(6)
	v_mfma_f32_32x32x16_bf16 v[32:47], v[200:203], v[216:219], v[32:47]
	ds_read_b64_tr_b16 v[216:217], v153 offset:0x2600
	ds_read_b64_tr_b16 v[218:219], v153 offset:0x2e00
	v_exp_f32_e32 v125, v80
	v_exp_f32_e32 v127, v81
	v_exp_f32_e32 v123, v82
	s_waitcnt lgkmcnt(6)
	v_mfma_f32_32x32x16_bf16 v[32:47], v[204:207], v[220:223], v[32:47]
	ds_read_b64_tr_b16 v[220:221], v153 offset:0x3600
	ds_read_b64_tr_b16 v[222:223], v153 offset:0x3e00
	v_exp_f32_e32 v126, v83
	v_exp_f32_e32 v122, v84
	s_waitcnt lgkmcnt(6)
	v_mfma_f32_32x32x16_bf16 v[16:31], v[196:199], v[208:211], v[16:31]
	v_exp_f32_e32 v124, v85
	v_exp_f32_e32 v120, v86
	v_exp_f32_e32 v121, v87
	s_waitcnt lgkmcnt(4)
	v_mfma_f32_32x32x16_bf16 v[16:31], v[192:195], v[212:215], v[16:31]
	v_exp_f32_e32 v117, v88
	v_exp_f32_e32 v119, v89
	v_exp_f32_e32 v116, v90
	s_waitcnt lgkmcnt(2)
	v_mfma_f32_32x32x16_bf16 v[16:31], v[200:203], v[216:219], v[16:31]
	v_exp_f32_e32 v118, v91
	v_exp_f32_e32 v113, v92
	s_waitcnt lgkmcnt(0)
	v_mfma_f32_32x32x16_bf16 v[16:31], v[204:207], v[220:223], v[16:31]
	v_exp_f32_e32 v115, v93
	v_exp_f32_e32 v112, v94
	v_exp_f32_e32 v114, v95
	v_cndmask_b32_e64 v191, v134, 1.0, s[4:5]
	v_cmp_gt_f32_e32 vcc, 1.0, v191
	s_cbranch_vccz .LBB0_308
	s_and_saveexec_b64 s[8:9], s[6:7]
	ds_write_b32 v150, v191 offset:128
	s_or_b64 exec, exec, s[8:9]
	s_waitcnt lgkmcnt(0)
	v_add_u32_e32 v228, v139, v136
	ds_read_b128 v[208:211], v228 offset:224
	ds_read_b128 v[212:215], v228 offset:192
	ds_read_b128 v[216:219], v228 offset:160
	ds_read_b128 v[220:223], v228 offset:128
	s_waitcnt lgkmcnt(3)
	v_pk_mul_f32 v[12:13], v[12:13], v[208:209]
	s_waitcnt lgkmcnt(2)
	v_pk_mul_f32 v[8:9], v[8:9], v[212:213]
	s_waitcnt lgkmcnt(1)
	v_pk_mul_f32 v[4:5], v[4:5], v[216:217]
	v_pk_mul_f32 v[14:15], v[14:15], v[210:211]
	v_pk_mul_f32 v[10:11], v[10:11], v[214:215]
	v_pk_mul_f32 v[6:7], v[6:7], v[218:219]
	s_waitcnt lgkmcnt(0)
	v_pk_mul_f32 v[2:3], v[2:3], v[222:223]
	v_pk_mul_f32 v[0:1], v[0:1], v[220:221]
	v_pk_mul_f32 v[60:61], v[60:61], v[208:209]
	v_pk_mul_f32 v[56:57], v[56:57], v[212:213]
	v_pk_mul_f32 v[52:53], v[52:53], v[216:217]
	v_pk_mul_f32 v[62:63], v[62:63], v[210:211]
	v_pk_mul_f32 v[58:59], v[58:59], v[214:215]
	v_pk_mul_f32 v[54:55], v[54:55], v[218:219]
	v_pk_mul_f32 v[50:51], v[50:51], v[222:223]
	v_pk_mul_f32 v[48:49], v[48:49], v[220:221]
	v_pk_mul_f32 v[44:45], v[44:45], v[208:209]
	v_pk_mul_f32 v[40:41], v[40:41], v[212:213]
	v_pk_mul_f32 v[36:37], v[36:37], v[216:217]
	v_pk_mul_f32 v[46:47], v[46:47], v[210:211]
	v_pk_mul_f32 v[42:43], v[42:43], v[214:215]
	v_pk_mul_f32 v[38:39], v[38:39], v[218:219]
	v_pk_mul_f32 v[34:35], v[34:35], v[222:223]
	v_pk_mul_f32 v[32:33], v[32:33], v[220:221]
	v_pk_mul_f32 v[28:29], v[28:29], v[208:209]
	v_pk_mul_f32 v[24:25], v[24:25], v[212:213]
	v_pk_mul_f32 v[20:21], v[20:21], v[216:217]
	v_pk_mul_f32 v[30:31], v[30:31], v[210:211]
	v_pk_mul_f32 v[26:27], v[26:27], v[214:215]
	v_pk_mul_f32 v[22:23], v[22:23], v[218:219]
	v_pk_mul_f32 v[18:19], v[18:19], v[222:223]
	v_pk_mul_f32 v[16:17], v[16:17], v[220:221]
